# HGRN pass A too: loads interleaved through step 2; grid barrier leader releases XCD flag before its own invalidate
# speedup vs baseline: 1.0015x; 1.0015x over previous
; __device__ __forceinline__ unsigned xb_add(unsigned* p, unsigned v) { return __hip_atomic_fetch_add(p, v, __ATOMIC_RELAXED, __HIP_MEMORY_SCOPE_AGENT); }
; __device__ __forceinline__ void xcd_barrier(unsigned* bar, volatile LAS unsigned* st) {
;     ...
;       __builtin_amdgcn_fence(__ATOMIC_ACQUIRE, "agent");
;       xb_add(&bar[XB_XGEN(x)], 1u);
;       asm volatile("s_waitcnt vmcnt(0)" ::: "memory");
.LBB0_208:
	s_or_b64 exec, exec, s[0:1]
	s_mov_b64 s[0:1], exec
	v_mbcnt_lo_u32_b32 v0, s0, 0
	v_mbcnt_hi_u32_b32 v0, s1, v0
	v_cmp_eq_u32_e32 vcc, 0, v0
	s_waitcnt vmcnt(0)
	s_and_saveexec_b64 s[2:3], vcc
	s_cbranch_execz .LBB0_210
	s_bcnt1_i32_b64 s0, s[0:1]
	v_mov_b32_e32 v0, 0x2000
	v_mov_b32_e32 v1, s0
	global_atomic_add v0, v1, s[10:11] offset:1024
.LBB0_210:
	s_or_b64 exec, exec, s[2:3]
	buffer_inv sc1
	s_waitcnt vmcnt(0)

; __device__ __forceinline__ unsigned xb_add(unsigned* p, unsigned v) { return __hip_atomic_fetch_add(p, v, __ATOMIC_RELAXED, __HIP_MEMORY_SCOPE_AGENT); }
; __device__ __forceinline__ void xcd_barrier(unsigned* bar, volatile LAS unsigned* st) {
;     ...
;       __builtin_amdgcn_fence(__ATOMIC_ACQUIRE, "agent");
;       xb_add(&bar[XB_XGEN(x)], 1u);
;       asm volatile("s_waitcnt vmcnt(0)" ::: "memory");
.LBB0_276:
	s_or_b64 exec, exec, s[0:1]
	s_mov_b64 s[0:1], exec
	v_mbcnt_lo_u32_b32 v0, s0, 0
	v_mbcnt_hi_u32_b32 v0, s1, v0
	v_cmp_eq_u32_e32 vcc, 0, v0
	s_waitcnt vmcnt(0)
	s_and_saveexec_b64 s[2:3], vcc
	s_cbranch_execz .LBB0_278
	s_bcnt1_i32_b64 s0, s[0:1]
	v_mov_b32_e32 v0, 0x2000
	v_mov_b32_e32 v1, s0
	global_atomic_add v0, v1, s[8:9] offset:1024

; __device__ __forceinline__ unsigned xb_add(unsigned* p, unsigned v) { return __hip_atomic_fetch_add(p, v, __ATOMIC_RELAXED, __HIP_MEMORY_SCOPE_AGENT); }
; __device__ __forceinline__ void xcd_barrier(unsigned* bar, volatile LAS unsigned* st) {
;     ...
;       __builtin_amdgcn_fence(__ATOMIC_ACQUIRE, "agent");
;       xb_add(&bar[XB_XGEN(x)], 1u);
;       asm volatile("s_waitcnt vmcnt(0)" ::: "memory");
.LBB0_370:
	s_or_b64 exec, exec, s[0:1]
	s_mov_b64 s[0:1], exec
	v_mbcnt_lo_u32_b32 v0, s0, 0
	v_mbcnt_hi_u32_b32 v0, s1, v0
	v_cmp_eq_u32_e32 vcc, 0, v0
	s_waitcnt vmcnt(0)
	s_and_saveexec_b64 s[2:3], vcc
	s_cbranch_execz .LBB0_372
	s_bcnt1_i32_b64 s0, s[0:1]
	v_mov_b32_e32 v0, 0x2000
	v_mov_b32_e32 v1, s0
	global_atomic_add v0, v1, s[6:7] offset:1024

; __device__ __forceinline__ float bf2f(bf16_t v) { return __uint_as_float(((unsigned)v) << 16); }
; #define LAS __attribute__((address_space(3)))
; template <bool OUT>
; __device__ void phase_hgrn(const Params& p, const bf16_t* Qh, const bf16_t* Vv, const _Float16* Lfb, bf16_t* Of, bf16_t* Ob, float* Sseg, float* Dlog, LAS unsigned char* lds) {
;     ...
; #pragma unroll
;       for (int i = 0; i < 16; ++i) { lf[i] = (float)lfr[i]; run += lf[i]; cs[i] = run; }
;       *(LAS float*)(lds + TOT + (tq * 128 + dk) * 4) = run;
;       __syncthreads();
;       float offs = 0.f, blast = 0.f;
; #pragma unroll
;       for (int g = 0; g < 4; ++g) { const float t = *(const LAS float*)(lds + TOT + (g * 128 + dk) * 4); blast += t; if (g < tq) offs += t; }
;       {
;         const float eblast = __expf(blast);
;         unsigned kew[8], vw[8];
; #pragma unroll
;         for (int i = 0; i < 16; i += 2) {
;           float qt[2], kt[2], ke[2];
; #pragma unroll
;           for (int e = 0; e < 2; ++e) {
;             const float bb = offs + cs[i + e];
;             const float k = 1.f - __expf(lf[i + e]);
;             const float ken = k * __expf(-bb);
;             if constexpr (OUT) { qt[e] = bf2f(qr[i + e]) * __expf(bb); kt[e] = ken; }
;             ke[e] = ken * eblast;
;           }
;     ...
;         const int cn = c + 1;
;         const int rb = (cn < 4) ? b * 256 + (dir ? 255 - 64 * cn : 64 * cn) : NCTX + b * 8192 + (dir ? 8191 - 64 * (cn - 4) : 64 * (cn - 4));
;         const size_t o0 = (size_t)(rb + sgn * 16 * tq) * DM + h * 128 + dk;
; #pragma unroll
;         for (int i = 0; i < 16; ++i) { const size_t o = o0 + (ptrdiff_t)(sgn * i) * DM; lfr[i] = Lx[o]; if constexpr (OUT) qr[i] = Qh[o]; else qr[i] = 0; vr[i] = Vv[o]; }
.LBB0_2209:
	s_add_i32 s99, s63, 1
	s_cmp_ge_i32 s99, s62
	s_cbranch_scc1 .Lhga_keep
	s_add_i32 s99, s2, s54
	s_cmp_gt_i32 s63, 2
	s_cbranch_scc0 .Lhga_ctx
	s_add_i32 s98, s99, 0xffffff40
	s_and_b64 s[100:101], s[18:19], exec
	s_cselect_b32 s98, s98, s3
	s_add_i32 s98, s98, s17
	s_branch .Lhga_keep
.Lhga_ctx:
	s_add_i32 s99, s99, 64
	s_add_i32 s98, s3, 0xffffe000
	s_and_b64 s[100:101], s[18:19], exec
	s_cselect_b32 s98, s99, s98
	s_add_i32 s98, s98, s61
.Lhga_keep:
	v_add_u32_e32 v228, s98, v61
	v_ashrrev_i32_e32 v229, 31, v228
	v_lshlrev_b64 v[228:229], 11, v[228:229]
	v_lshl_or_b32 v228, v52, 1, v228
	v_lshl_add_u64 v[230:231], s[20:21], 0, v[228:229]
	v_lshl_add_u64 v[234:235], s[14:15], 0, v[228:229]
	v_cvt_f32_f16_e32 v54, v62
	v_cvt_f32_f16_e32 v83, v63
	v_cvt_f32_f16_e32 v84, v64
	v_cvt_f32_f16_e32 v85, v65
	v_add_f32_e32 v82, 0, v54
	v_cvt_f32_f16_e32 v89, v66
	v_add_f32_e32 v86, v82, v83
	v_cvt_f32_f16_e32 v90, v67
	v_add_f32_e32 v87, v86, v84
	v_cvt_f32_f16_e32 v91, v68
	v_add_f32_e32 v88, v87, v85
	v_cvt_f32_f16_e32 v92, v69
	v_add_f32_e32 v93, v88, v89
	v_cvt_f32_f16_e32 v97, v70
	v_add_f32_e32 v94, v93, v90
	v_cvt_f32_f16_e32 v98, v71
	v_add_f32_e32 v95, v94, v91
	v_cvt_f32_f16_e32 v99, v72
	v_add_f32_e32 v96, v95, v92
	v_cvt_f32_f16_e32 v100, v73
	v_add_f32_e32 v101, v96, v97
	v_cvt_f32_f16_e32 v105, v74
	v_add_f32_e32 v102, v101, v98
	v_cvt_f32_f16_e32 v106, v75
	v_add_f32_e32 v103, v102, v99
	v_cvt_f32_f16_e32 v107, v76
	v_add_f32_e32 v104, v103, v100
	s_waitcnt vmcnt(0)
	v_cvt_f32_f16_e32 v108, v77
	v_add_f32_e32 v109, v104, v105
	v_add_f32_e32 v110, v109, v106
	v_add_f32_e32 v111, v110, v107
	v_add_f32_e32 v112, v111, v108
	v_add_u32_e32 v80, s60, v44
	ds_write_b32 v59, v112
	s_waitcnt lgkmcnt(0)
	s_barrier
	ds_read2st64_b32 v[78:79], v80 offset1:2
	ds_read2st64_b32 v[80:81], v80 offset0:4 offset1:6
	v_mul_f32_e32 v54, 0x3fb8aa3b, v54
	s_waitcnt lgkmcnt(1)
	v_add_f32_e32 v78, 0, v78
	v_cndmask_b32_e64 v113, v78, 0, s[6:7]
	global_load_ushort v180, v[230:231], off
	v_add_f32_e32 v78, v78, v79
	v_add_f32_e32 v79, v79, v113
	v_cndmask_b32_e64 v79, v113, v79, s[8:9]
	s_waitcnt lgkmcnt(0)
	global_load_ushort v212, v[234:235], off
	v_lshl_add_u64 v[236:237], v[230:231], 0, s[22:23]
	v_add_f32_e32 v78, v78, v80
	v_add_f32_e32 v80, v80, v79
	v_cndmask_b32_e64 v79, v79, v80, s[10:11]
	v_add_f32_e32 v80, v81, v79
	global_load_ushort v181, v[236:237], off
	v_lshl_add_u64 v[238:239], v[234:235], 0, s[22:23]
	v_cndmask_b32_e64 v79, v79, v80, s[12:13]
	v_add_f32_e32 v78, v78, v81
	v_add_f32_e32 v81, v82, v79
	v_exp_f32_e32 v80, v54
	global_load_ushort v213, v[238:239], off
	v_lshl_add_u64 v[240:241], v[230:231], 0, s[24:25]
	v_mul_f32_e32 v54, 0xbfb8aa3b, v81
	v_exp_f32_e32 v82, v54
	v_add_f32_e32 v54, v86, v79
	v_mul_f32_e32 v81, 0x3fb8aa3b, v83
	global_load_ushort v182, v[240:241], off
	v_lshl_add_u64 v[242:243], v[234:235], 0, s[24:25]
	v_exp_f32_e32 v81, v81
	v_mul_f32_e32 v54, 0xbfb8aa3b, v54
	v_exp_f32_e32 v83, v54
	v_mul_f32_e32 v54, 0x3fb8aa3b, v78
	global_load_ushort v214, v[242:243], off
	v_lshl_add_u64 v[236:237], v[230:231], 0, s[26:27]
	v_pk_add_f32 v[80:81], v[80:81], 1.0 op_sel_hi:[1,0] neg_lo:[1,0] neg_hi:[1,0]
	v_exp_f32_e32 v54, v54
	v_pk_mul_f32 v[80:81], v[80:81], v[82:83]
	v_add_f32_e32 v83, v87, v79
	global_load_ushort v183, v[236:237], off
	v_lshl_add_u64 v[238:239], v[234:235], 0, s[26:27]
	v_mul_f32_e32 v83, 0xbfb8aa3b, v83
	v_mul_f32_e32 v82, 0x3fb8aa3b, v84
	v_exp_f32_e32 v84, v83
	v_add_f32_e32 v86, v88, v79
	global_load_ushort v215, v[238:239], off
	v_lshl_add_u64 v[240:241], v[230:231], 0, s[28:29]
	v_mul_f32_e32 v83, 0x3fb8aa3b, v85
	v_exp_f32_e32 v82, v82
	v_exp_f32_e32 v83, v83
	v_mul_f32_e32 v85, 0xbfb8aa3b, v86
	global_load_ushort v184, v[240:241], off
	v_lshl_add_u64 v[242:243], v[234:235], 0, s[28:29]
	v_exp_f32_e32 v85, v85
	v_pk_mul_f32 v[80:81], v[54:55], v[80:81] op_sel_hi:[0,1]
	v_cvt_pk_bf16_f32 v80, v80, v81
	v_pk_add_f32 v[82:83], v[82:83], 1.0 op_sel_hi:[1,0] neg_lo:[1,0] neg_hi:[1,0]
	global_load_ushort v216, v[242:243], off
	v_lshl_add_u64 v[236:237], v[230:231], 0, s[30:31]
	v_add_f32_e32 v81, v93, v79
	v_pk_mul_f32 v[82:83], v[82:83], v[84:85]
	v_mul_f32_e32 v84, 0x3fb8aa3b, v89
	global_load_ushort v185, v[236:237], off
	v_lshl_add_u64 v[238:239], v[234:235], 0, s[30:31]
	v_mul_f32_e32 v81, 0xbfb8aa3b, v81
	v_mul_f32_e32 v85, 0x3fb8aa3b, v90
	v_exp_f32_e32 v84, v84
	v_exp_f32_e32 v86, v81
	global_load_ushort v217, v[238:239], off
	v_lshl_add_u64 v[240:241], v[230:231], 0, s[34:35]
	v_add_f32_e32 v81, v94, v79
	v_exp_f32_e32 v85, v85
	v_mul_f32_e32 v81, 0xbfb8aa3b, v81
	v_exp_f32_e32 v87, v81
	global_load_ushort v186, v[240:241], off
	v_lshl_add_u64 v[242:243], v[234:235], 0, s[34:35]
	v_pk_mul_f32 v[82:83], v[54:55], v[82:83] op_sel_hi:[0,1]
	v_cvt_pk_bf16_f32 v81, v82, v83
	v_pk_add_f32 v[82:83], v[84:85], 1.0 op_sel_hi:[1,0] neg_lo:[1,0] neg_hi:[1,0]
	v_add_f32_e32 v85, v95, v79
	global_load_ushort v218, v[242:243], off
	v_lshl_add_u64 v[236:237], v[230:231], 0, s[36:37]
	v_mul_f32_e32 v85, 0xbfb8aa3b, v85
	v_pk_mul_f32 v[82:83], v[82:83], v[86:87]
	v_mul_f32_e32 v84, 0x3fb8aa3b, v91
	v_exp_f32_e32 v86, v85
	global_load_ushort v187, v[236:237], off
	v_lshl_add_u64 v[238:239], v[234:235], 0, s[36:37]
	v_add_f32_e32 v87, v96, v79
	v_mul_f32_e32 v85, 0x3fb8aa3b, v92
	v_exp_f32_e32 v84, v84
	v_exp_f32_e32 v85, v85
	global_load_ushort v219, v[238:239], off
	v_lshl_add_u64 v[240:241], v[230:231], 0, s[38:39]
	v_mul_f32_e32 v87, 0xbfb8aa3b, v87
	v_exp_f32_e32 v87, v87
	v_pk_mul_f32 v[82:83], v[54:55], v[82:83] op_sel_hi:[0,1]
	v_cvt_pk_bf16_f32 v82, v82, v83
	global_load_ushort v188, v[240:241], off
; __device__ __forceinline__ float bf2f(bf16_t v) { return __uint_as_float(((unsigned)v) << 16); }
; __device__ __forceinline__ unsigned pk2(float lo, float hi) { f32x2 v = {lo, hi}; return __builtin_bit_cast(unsigned, __builtin_convertvector(v, bf16v2)); }
; #define LAS __attribute__((address_space(3)))
; template <bool OUT>
; __device__ void phase_hgrn(const Params& p, const bf16_t* Qh, const bf16_t* Vv, const _Float16* Lfb, bf16_t* Of, bf16_t* Ob, float* Sseg, float* Dlog, LAS unsigned char* lds) {
;     ...
;         for (int i = 0; i < 16; i += 2) {
;           float qt[2], kt[2], ke[2];
; #pragma unroll
;           for (int e = 0; e < 2; ++e) {
;             const float bb = offs + cs[i + e];
;             const float k = 1.f - __expf(lf[i + e]);
;             const float ken = k * __expf(-bb);
;             if constexpr (OUT) { qt[e] = bf2f(qr[i + e]) * __expf(bb); kt[e] = ken; }
;             ke[e] = ken * eblast;
;           }
;           if constexpr (OUT) {
;             const unsigned qp = pk2(qt[0], qt[1]), kp = pk2(kt[0], kt[1]);
;             const int s = 16 * tq + i;
;             *(LAS bf16_t*)(lds + QT + (s * 136 + dk) * 2) = (bf16_t)(qp & 0xffffu);
;             *(LAS bf16_t*)(lds + QT + ((s + 1) * 136 + dk) * 2) = (bf16_t)(qp >> 16);
;             *(LAS bf16_t*)(lds + KT + (s * 136 + dk) * 2) = (bf16_t)(kp & 0xffffu);
;             *(LAS bf16_t*)(lds + KT + ((s + 1) * 136 + dk) * 2) = (bf16_t)(kp >> 16);
;           }
;           kew[i >> 1] = pk2(ke[0], ke[1]);
;           vw[i >> 1] = (unsigned)vr[i] | ((unsigned)vr[i + 1] << 16);
;         }
;         *(LAS u32x4*)(lds + KE + (dk * 72 + 16 * tq) * 2) = (u32x4){kew[0], kew[1], kew[2], kew[3]};
;         *(LAS u32x4*)(lds + KE + (dk * 72 + 16 * tq + 8) * 2) = (u32x4){kew[4], kew[5], kew[6], kew[7]};
;         *(LAS u32x4*)(lds + VT + (dk * 72 + 16 * tq) * 2) = (u32x4){vw[0], vw[1], vw[2], vw[3]};
;         *(LAS u32x4*)(lds + VT + (dk * 72 + 16 * tq + 8) * 2) = (u32x4){vw[4], vw[5], vw[6], vw[7]};
;         if (tq == 0) *(LAS float*)(lds + DC + dk * 4) = eblast;
;         dsum += blast;
;       }
;       __syncthreads();
	v_lshl_add_u64 v[242:243], v[234:235], 0, s[38:39]
	v_pk_add_f32 v[84:85], v[84:85], 1.0 op_sel_hi:[1,0] neg_lo:[1,0] neg_hi:[1,0]
	v_add_f32_e32 v83, v101, v79
	v_pk_mul_f32 v[84:85], v[84:85], v[86:87]
	v_mul_f32_e32 v86, 0x3fb8aa3b, v97
	global_load_ushort v220, v[242:243], off
	v_lshl_add_u64 v[236:237], v[230:231], 0, s[40:41]
	v_mul_f32_e32 v83, 0xbfb8aa3b, v83
	v_mul_f32_e32 v87, 0x3fb8aa3b, v98
	v_exp_f32_e32 v86, v86
	v_exp_f32_e32 v88, v83
	global_load_ushort v189, v[236:237], off
	v_lshl_add_u64 v[238:239], v[234:235], 0, s[40:41]
	v_add_f32_e32 v83, v102, v79
	v_exp_f32_e32 v87, v87
	v_mul_f32_e32 v83, 0xbfb8aa3b, v83
	v_exp_f32_e32 v89, v83
	global_load_ushort v221, v[238:239], off
	v_lshl_add_u64 v[240:241], v[230:231], 0, s[42:43]
	v_pk_mul_f32 v[84:85], v[54:55], v[84:85] op_sel_hi:[0,1]
	v_cvt_pk_bf16_f32 v83, v84, v85
	v_pk_add_f32 v[84:85], v[86:87], 1.0 op_sel_hi:[1,0] neg_lo:[1,0] neg_hi:[1,0]
	v_add_f32_e32 v87, v103, v79
	global_load_ushort v190, v[240:241], off
	v_lshl_add_u64 v[242:243], v[234:235], 0, s[42:43]
	v_mul_f32_e32 v87, 0xbfb8aa3b, v87
	v_pk_mul_f32 v[84:85], v[84:85], v[88:89]
	v_mul_f32_e32 v86, 0x3fb8aa3b, v99
	global_load_ushort v222, v[242:243], off
	v_lshl_add_u64 v[236:237], v[230:231], 0, s[44:45]
	v_exp_f32_e32 v88, v87
	v_add_f32_e32 v89, v104, v79
	v_mul_f32_e32 v87, 0x3fb8aa3b, v100
	v_exp_f32_e32 v86, v86
	global_load_ushort v191, v[236:237], off
	v_lshl_add_u64 v[238:239], v[234:235], 0, s[44:45]
	v_exp_f32_e32 v87, v87
	v_mul_f32_e32 v89, 0xbfb8aa3b, v89
	v_exp_f32_e32 v89, v89
	v_pk_mul_f32 v[84:85], v[54:55], v[84:85] op_sel_hi:[0,1]
	global_load_ushort v223, v[238:239], off
	v_lshl_add_u64 v[240:241], v[230:231], 0, s[46:47]
	v_cvt_pk_bf16_f32 v84, v84, v85
	v_pk_add_f32 v[86:87], v[86:87], 1.0 op_sel_hi:[1,0] neg_lo:[1,0] neg_hi:[1,0]
	v_add_f32_e32 v85, v109, v79
	v_pk_mul_f32 v[86:87], v[86:87], v[88:89]
	global_load_ushort v192, v[240:241], off
	v_lshl_add_u64 v[242:243], v[234:235], 0, s[46:47]
	v_mul_f32_e32 v88, 0x3fb8aa3b, v105
	v_mul_f32_e32 v85, 0xbfb8aa3b, v85
	v_mul_f32_e32 v89, 0x3fb8aa3b, v106
	v_exp_f32_e32 v88, v88
	global_load_ushort v224, v[242:243], off
	v_lshl_add_u64 v[236:237], v[230:231], 0, s[48:49]
	v_exp_f32_e32 v90, v85
	v_add_f32_e32 v85, v110, v79
	v_exp_f32_e32 v89, v89
	v_mul_f32_e32 v85, 0xbfb8aa3b, v85
	global_load_ushort v193, v[236:237], off
	v_lshl_add_u64 v[238:239], v[234:235], 0, s[48:49]
	v_exp_f32_e32 v91, v85
	v_pk_mul_f32 v[86:87], v[54:55], v[86:87] op_sel_hi:[0,1]
	v_cvt_pk_bf16_f32 v85, v86, v87
	v_pk_add_f32 v[86:87], v[88:89], 1.0 op_sel_hi:[1,0] neg_lo:[1,0] neg_hi:[1,0]
	global_load_ushort v225, v[238:239], off
	v_lshl_add_u64 v[240:241], v[230:231], 0, s[50:51]
	v_add_f32_e32 v89, v111, v79
	v_mul_f32_e32 v89, 0xbfb8aa3b, v89
	v_pk_mul_f32 v[86:87], v[86:87], v[90:91]
	v_mul_f32_e32 v88, 0x3fb8aa3b, v107
	global_load_ushort v194, v[240:241], off
	v_lshl_add_u64 v[242:243], v[234:235], 0, s[50:51]
	v_exp_f32_e32 v90, v89
	v_add_f32_e32 v79, v112, v79
	v_mul_f32_e32 v89, 0x3fb8aa3b, v108
	v_exp_f32_e32 v88, v88
	global_load_ushort v226, v[242:243], off
	v_lshl_add_u64 v[236:237], v[230:231], 0, s[52:53]
	v_exp_f32_e32 v89, v89
	v_mul_f32_e32 v79, 0xbfb8aa3b, v79
	v_exp_f32_e32 v91, v79
	v_pk_mul_f32 v[86:87], v[54:55], v[86:87] op_sel_hi:[0,1]
	global_load_ushort v195, v[236:237], off
	v_lshl_add_u64 v[238:239], v[234:235], 0, s[52:53]
	v_pk_add_f32 v[88:89], v[88:89], 1.0 op_sel_hi:[1,0] neg_lo:[1,0] neg_hi:[1,0]
	v_cvt_pk_bf16_f32 v86, v86, v87
	v_pk_mul_f32 v[88:89], v[88:89], v[90:91]
	s_nop 0
	global_load_ushort v227, v[238:239], off
	v_pk_mul_f32 v[88:89], v[54:55], v[88:89] op_sel_hi:[0,1]
	v_cvt_pk_bf16_f32 v87, v88, v89
	ds_write_b128 v55, v[80:83] offset:34816
	ds_write_b128 v55, v[84:87] offset:34832
	ds_write_b128 v55, v[32:35] offset:53248
	ds_write_b128 v55, v[36:39] offset:53264
	s_and_saveexec_b64 s[0:1], s[6:7]
	v_add_u32_e32 v79, 0, v53
	v_add_u32_e32 v79, 0x1c400, v79
	ds_write_b32 v79, v54
	s_or_b64 exec, exec, s[0:1]
	s_add_i32 s4, s63, 1
	s_cmp_ge_i32 s4, s62
	s_waitcnt lgkmcnt(0)
	s_barrier
; #define LAS __attribute__((address_space(3)))
; template <bool OUT>
; __device__ void phase_hgrn(const Params& p, const bf16_t* Qh, const bf16_t* Vv, const _Float16* Lfb, bf16_t* Of, bf16_t* Ob, float* Sseg, float* Dlog, LAS unsigned char* lds) {
;     ...
;       if (c + 1 < c_end) {
;         const int cn = c + 1;
;         const int rb = (cn < 4) ? b * 256 + (dir ? 255 - 64 * cn : 64 * cn) : NCTX + b * 8192 + (dir ? 8191 - 64 * (cn - 4) : 64 * (cn - 4));
;         const size_t o0 = (size_t)(rb + sgn * 16 * tq) * DM + h * 128 + dk;
; #pragma unroll
;         for (int i = 0; i < 16; ++i) { const size_t o = o0 + (ptrdiff_t)(sgn * i) * DM; lfr[i] = Lx[o]; if constexpr (OUT) qr[i] = Qh[o]; else qr[i] = 0; vr[i] = Vv[o]; }
;       }
;     ...
;       {
; #pragma unroll
;         for (int g = 0; g < 4; ++g) {
;           const f32x4 d0 = *(const LAS f32x4*)(lds + DC + (32 * (2 * wh) + 8 * g + 4 * hh) * 4);
;           const f32x4 d1 = *(const LAS f32x4*)(lds + DC + (32 * (2 * wh + 1) + 8 * g + 4 * hh) * 4);
; #pragma unroll
;           for (int j = 0; j < 4; ++j) { S0[4 * g + j] *= d0[j]; S1[4 * g + j] *= d1[j]; }
;         }
; #pragma unroll
;         for (int ks = 0; ks < 4; ++ks) {
;           const bf16x8 vb = *(const LAS bf16x8*)(lds + VT + ((32 * dvb + r) * 72 + 16 * ks + 8 * hh) * 2);
;           const bf16x8 k0 = *(const LAS bf16x8*)(lds + KE + ((32 * (2 * wh) + r) * 72 + 16 * ks + 8 * hh) * 2);
;           const bf16x8 k1 = *(const LAS bf16x8*)(lds + KE + ((32 * (2 * wh + 1) + r) * 72 + 16 * ks + 8 * hh) * 2);
;           S0 = __builtin_amdgcn_mfma_f32_32x32x16_bf16(k0, vb, S0, 0, 0, 0);
;           S1 = __builtin_amdgcn_mfma_f32_32x32x16_bf16(k1, vb, S1, 0, 0, 0);
;         }
;       }
.LBB0_2217:
	ds_read_b128 v[80:83], v56
	ds_read_b128 v[84:87], v56 offset:32
	ds_read_b128 v[88:91], v56 offset:64
	ds_read_b128 v[92:95], v56 offset:96
	ds_read_b128 v[96:99], v56 offset:128
	ds_read_b128 v[100:103], v56 offset:160
	ds_read_b128 v[104:107], v56 offset:192
	ds_read_b128 v[108:111], v56 offset:224
	v_add_u32_e32 v54, 0, v45
	s_waitcnt lgkmcnt(5)
	v_pk_mul_f32 v[8:9], v[8:9], v[88:89]
	v_pk_mul_f32 v[10:11], v[10:11], v[90:91]
	ds_read_b128 v[88:91], v54 offset:34816
	v_pk_mul_f32 v[0:1], v[0:1], v[80:81]
	v_pk_mul_f32 v[2:3], v[2:3], v[82:83]
	ds_read_b128 v[80:83], v57 offset:53248
	s_waitcnt lgkmcnt(6)
	v_pk_mul_f32 v[12:13], v[12:13], v[92:93]
	v_pk_mul_f32 v[4:5], v[4:5], v[84:85]
	v_pk_mul_f32 v[14:15], v[14:15], v[94:95]
	v_pk_mul_f32 v[6:7], v[6:7], v[86:87]
	ds_read_b128 v[84:87], v57 offset:53280
	ds_read_b128 v[92:95], v54 offset:34848
	ds_read_b128 v[112:115], v58 offset:34816
	s_waitcnt lgkmcnt(3)
	v_mfma_f32_32x32x16_bf16 v[0:15], v[88:91], v[80:83], v[0:15]
	v_mul_f32_e64 v28, v28, v108
	v_mul_f32_e64 v29, v29, v109
	v_mul_f32_e64 v24, v24, v104
	v_mul_f32_e64 v25, v25, v105
	v_mul_f32_e64 v20, v20, v100
	v_mul_f32_e64 v21, v21, v101
	v_pk_mul_f32 v[16:17], v[16:17], v[96:97]
	v_pk_mul_f32 v[30:31], v[30:31], v[110:111]
	v_pk_mul_f32 v[26:27], v[26:27], v[106:107]
	v_pk_mul_f32 v[22:23], v[22:23], v[102:103]
	v_pk_mul_f32 v[18:19], v[18:19], v[98:99]
	ds_read_b128 v[88:91], v58 offset:34848
	s_waitcnt lgkmcnt(2)
	v_mfma_f32_32x32x16_bf16 v[0:15], v[92:95], v[84:87], v[0:15]
	s_add_i32 s54, s54, 64
	s_sub_i32 s3, s3, 64
	v_add_f32_e32 v60, v60, v78
	s_cmpk_eq_i32 s54, 0x840
	s_waitcnt lgkmcnt(1)
	v_mfma_f32_32x32x16_bf16 v[16:31], v[112:115], v[80:83], v[16:31]
	s_waitcnt lgkmcnt(0)
	v_mfma_f32_32x32x16_bf16 v[16:31], v[88:91], v[84:87], v[16:31]
	ds_read_b128 v[80:83], v54 offset:34880
	ds_read_b128 v[84:87], v57 offset:53312
	ds_read_b128 v[88:91], v57 offset:53344
	ds_read_b128 v[92:95], v54 offset:34912
	s_waitcnt lgkmcnt(2)
	v_mfma_f32_32x32x16_bf16 v[0:15], v[80:83], v[84:87], v[0:15]
	ds_read_b128 v[80:83], v58 offset:34880
	ds_read_b128 v[96:99], v58 offset:34912
	s_waitcnt lgkmcnt(1)
	v_mfma_f32_32x32x16_bf16 v[16:31], v[80:83], v[84:87], v[16:31]
	v_mfma_f32_32x32x16_bf16 v[0:15], v[92:95], v[88:91], v[0:15]
	s_waitcnt lgkmcnt(0)
	v_mfma_f32_32x32x16_bf16 v[16:31], v[96:99], v[88:91], v[16:31]
	s_cbranch_scc1 .LBB0_2219
	s_waitcnt vmcnt(0)
	v_lshl_or_b32 v32, v213, 16, v212
	v_lshl_or_b32 v33, v215, 16, v214
	v_lshl_or_b32 v34, v217, 16, v216
	v_lshl_or_b32 v35, v219, 16, v218
	v_lshl_or_b32 v36, v221, 16, v220
	v_lshl_or_b32 v37, v223, 16, v222
	v_lshl_or_b32 v38, v225, 16, v224
	v_lshl_or_b32 v39, v227, 16, v226
	v_mov_b32_e32 v62, v180
	v_mov_b32_e32 v63, v181
	v_mov_b32_e32 v64, v182
	v_mov_b32_e32 v65, v183
	v_mov_b32_e32 v66, v184
	v_mov_b32_e32 v67, v185
	v_mov_b32_e32 v68, v186
	v_mov_b32_e32 v69, v187
	v_mov_b32_e32 v70, v188
	v_mov_b32_e32 v71, v189
	v_mov_b32_e32 v72, v190
	v_mov_b32_e32 v73, v191
	v_mov_b32_e32 v74, v192
	v_mov_b32_e32 v75, v193
	v_mov_b32_e32 v76, v194
	v_mov_b32_e32 v77, v195
	s_mov_b32 s63, s4
	s_branch .LBB0_2209
